# xcd_tile GEMM phases: blocks >= 256 take the tile 4 columns over in their 8x8 group (co-resident pair no longer shares the weight tile)
# speedup vs baseline: 1.0111x; 1.0111x over previous
; DEV int xcd_tile_items(int mtiles, int NT) { const int groups = ((mtiles + 7) >> 3) * (NT >> 3); return ((groups + 7) >> 3) * 8 * 64; }
; DEV void phase_gemm_pq(const Params& p, int layer, int M, char* smem) {
;   EpiBf epi{layer ? WSP(bf16_t, L1_PQ) : WSP(bf16_t, R_PQ), 2048};
;   const bf16_t* Bt = WSP(bf16_t, S_WPQ) + (size_t)layer * 2048 * LDH;
;   const int items = xcd_tile_items(M / 128, 16);
;   for (int item = blockIdx.x; item < items; item += gridDim.x) {
;     int mt, nt;
;     if (!xcd_tile(item, M / 128, 16, mt, nt)) continue;
;     gemm_tile(WSP(bf16_t, OFF_H), LDH, Bt, LDH, 1024, mt * 128, nt * 128, epi, smem);
;   }
.LBB0_175:
	v_readlane_b32 s0, v252, 42
	v_readlane_b32 s1, v252, 43
	s_andn2_b64 vcc, exec, s[0:1]
	s_cbranch_vccnz .LBB0_186
	s_add_u32 s6, s28, 0xc300000
	s_addc_u32 s7, s29, 0
	s_add_u32 s8, s28, 0xba00000
	s_addc_u32 s9, s29, 0
	s_add_u32 s10, s28, 0x4200000
	s_addc_u32 s11, s29, 0
	s_lshr_b32 s13, s51, 8
	s_lshl_b32 s13, s13, 5
	s_xor_b32 s0, s51, s13
	s_mov_b32 s1, s0
	s_branch .LBB0_179

; DEV int xcd_tile_items(int mtiles, int NT) { const int groups = ((mtiles + 7) >> 3) * (NT >> 3); return ((groups + 7) >> 3) * 8 * 64; }
; DEV void phase_gemm_out(const Params& p, int layer, char* smem) {
;   float* X = WSP(float, OFF_X);
;   EpiRes epi;
;   epi.X = X; epi.mod = WSP(float, S_MOD) + (size_t)layer * 3 * 6144;
;   const bf16_t* A; const bf16_t* Bt; int M;
;   if (layer == 0) { epi.xin_main = p.in[I_X]; epi.xin_ctx = p.in[I_CTX]; A = WSP(bf16_t, R_MIX); Bt = WSP(bf16_t, S_WOUT0); M = MT; }
;   else { epi.xin_main = X; epi.xin_ctx = X + (size_t)MM * 1024; A = WSP(bf16_t, OFF_H); Bt = WSP(bf16_t, S_WHGOUT); M = MM; }
;   const int items = xcd_tile_items(M / 128, 8);
;   for (int item = blockIdx.x; item < items; item += gridDim.x) {
;     int mt, nt;
;     if (!xcd_tile(item, M / 128, 8, mt, nt)) continue;
;     gemm_tile(A, LDH, Bt, LDH, 1024, mt * 128, nt * 128, epi, smem);
;   }
.LBB0_193:
	s_andn2_b64 vcc, exec, s[0:1]
	s_cbranch_vccnz .LBB0_269
	v_readlane_b32 s0, v252, 44
	v_readlane_b32 s1, v252, 45
	s_andn2_b64 vcc, exec, s[0:1]
	s_cbranch_vccnz .LBB0_269
	s_add_u32 s6, s28, 0xbf52000
	s_addc_u32 s7, s29, 0
	s_add_u32 s8, s28, 0x4000000
	s_addc_u32 s9, s29, 0
	s_add_u32 s10, s28, 0xb3a0000
	s_addc_u32 s11, s29, 0
	s_add_u32 s14, s28, 0x4200000
	s_addc_u32 s15, s29, 0
	s_lshr_b32 s13, s51, 8
	s_lshl_b32 s13, s13, 5
	s_xor_b32 s2, s51, s13
	s_lshl_b32 s3, s2, 4
	s_mov_b32 s12, s2
	s_branch .LBB0_198

; DEV int xcd_tile_items(int mtiles, int NT) { const int groups = ((mtiles + 7) >> 3) * (NT >> 3); return ((groups + 7) >> 3) * 8 * 64; }
; DEV void phase_gemm_pq(const Params& p, int layer, int M, char* smem) {
;   EpiBf epi{layer ? WSP(bf16_t, L1_PQ) : WSP(bf16_t, R_PQ), 2048};
;   const bf16_t* Bt = WSP(bf16_t, S_WPQ) + (size_t)layer * 2048 * LDH;
;   const int items = xcd_tile_items(M / 128, 16);
;   for (int item = blockIdx.x; item < items; item += gridDim.x) {
;     int mt, nt;
;     if (!xcd_tile(item, M / 128, 16, mt, nt)) continue;
;     gemm_tile(WSP(bf16_t, OFF_H), LDH, Bt, LDH, 1024, mt * 128, nt * 128, epi, smem);
;   }
.LBB0_639:
	s_andn2_b64 vcc, exec, s[0:1]
	s_cbranch_vccnz .LBB0_651
	v_readlane_b32 s0, v252, 50
	v_readlane_b32 s1, v252, 51
	s_andn2_b64 vcc, exec, s[0:1]
	s_cbranch_vccnz .LBB0_651
	s_add_u32 s0, s28, 0x10300000
	s_addc_u32 s1, s29, 0
	s_add_u32 s2, s28, 0xb5c0000
	s_addc_u32 s3, s29, 0
	s_add_u32 s6, s28, 0x4200000
	s_addc_u32 s7, s29, 0
	s_lshr_b32 s13, s51, 8
	s_lshl_b32 s13, s13, 5
	s_xor_b32 s10, s51, s13
	s_mov_b32 s11, s10
	s_branch .LBB0_644

; DEV int xcd_tile_items(int mtiles, int NT) { const int groups = ((mtiles + 7) >> 3) * (NT >> 3); return ((groups + 7) >> 3) * 8 * 64; }
; DEV void phase_gemm_out(const Params& p, int layer, char* smem) {
;   float* X = WSP(float, OFF_X);
;   EpiRes epi;
;   epi.X = X; epi.mod = WSP(float, S_MOD) + (size_t)layer * 3 * 6144;
;   const bf16_t* A; const bf16_t* Bt; int M;
;   if (layer == 0) { epi.xin_main = p.in[I_X]; epi.xin_ctx = p.in[I_CTX]; A = WSP(bf16_t, R_MIX); Bt = WSP(bf16_t, S_WOUT0); M = MT; }
;   else { epi.xin_main = X; epi.xin_ctx = X + (size_t)MM * 1024; A = WSP(bf16_t, OFF_H); Bt = WSP(bf16_t, S_WHGOUT); M = MM; }
;   const int items = xcd_tile_items(M / 128, 8);
;   for (int item = blockIdx.x; item < items; item += gridDim.x) {
;     int mt, nt;
;     if (!xcd_tile(item, M / 128, 8, mt, nt)) continue;
;     gemm_tile(A, LDH, Bt, LDH, 1024, mt * 128, nt * 128, epi, smem);
;   }
.LBB0_662:
	s_andn2_b64 vcc, exec, s[0:1]
	s_cbranch_vccnz .LBB0_771
	s_cmp_gt_i32 s57, 5
	s_mov_b64 s[0:1], -1
	s_cbranch_scc0 .LBB0_740
	v_readlane_b32 s0, v252, 52
	v_readlane_b32 s1, v252, 53
	s_andn2_b64 vcc, exec, s[0:1]
	s_cbranch_vccnz .LBB0_739
	s_add_u32 s0, s28, 0xbf40000
	s_addc_u32 s1, s29, 0
	s_add_u32 s2, s28, 0xa6e0000
	s_addc_u32 s3, s29, 0
	s_add_u32 s6, s28, 0x19700000
	s_addc_u32 s7, s29, 0
	s_lshr_b32 s13, s51, 8
	s_lshl_b32 s13, s13, 5
	s_xor_b32 s10, s51, s13
	s_lshl_b32 s11, s10, 4
	s_mov_b32 s12, s10
	s_branch .LBB0_668
